# DIFF attention: eliminate per-sub-tile O accumulator copies (register bank swap in PV tail), + compress pipelining + P4 order
# speedup vs baseline: 1.0159x; 1.0159x over previous
; DI float ex2(float x) { return __builtin_amdgcn_exp2f(x); }
; template <int MM> DI void smax_step(const f32x16& s, unsigned vm, float& m, float& l, f32x16 (&o)[2], bf16x8 (&pf)[2], int lane) {
;     float t[16], mx = -1e30f;
; #pragma unroll
;     for (int i = 0; i < 16; ++i) { t[i] = (MM == 0) ? s[i] : (MM == 1 ? (vm ? s[i] : -1e30f) : (((vm >> i) & 1u) ? s[i] : -1e30f)); mx = fmaxf(mx, t[i]); }
;     mx = fmaxf(mx, shx32(mx, lane));
;     const float mn = (mx > m + 8.0f) ? mx : m;
;     const float mref = fmaxf(mn, -1e29f);
;     float p[16], rs = 0.f;
; #pragma unroll
;     for (int i = 0; i < 16; ++i) { p[i] = ex2(t[i] - mref); rs += p[i]; }
;     rs += shx32(rs, lane);
;     if (__builtin_amdgcn_ballot_w64(mn != m) != 0ull) {
;         const float alpha = ex2(m - mn);
;         l *= alpha;
; #pragma unroll
;         for (int i = 0; i < 16; ++i) { o[0][i] *= alpha; o[1][i] *= alpha; }
;         m = mn;
;     }
;     l += rs;
;     pack_p(p, pf);
; template <int MODE, bool PRE = false> ...
;     ...
;                 const f32x16 s1 = qk_rows<0, 2>(Kl, 32 * sub, qf, r, h), s2 = qk_rows<2, 4>(Kl, 32 * sub, qf, r, h);
;                 bf16x8 pf2[2];
;                 if (mm == 0) { smax_step<0>(s1, vm, m1, l1, o1, pf, lane); smax_step<0>(s2, vm, m2, l2, o2, pf2, lane); }
;                 else { smax_step<2>(s1, vm, m1, l1, o1, pf, lane); smax_step<2>(s2, vm, m2, l2, o2, pf2, lane); }
.LBB0_791:
	s_andn2_b64 vcc, exec, s[38:39]
	s_cbranch_vccnz .LBB0_804
	v_add_u32_e32 v33, v227, v221
	ds_read_b128 v[34:37], v33
	ds_read_b128 v[38:41], v33 offset:32
	s_setprio 1
	s_waitcnt lgkmcnt(1)
	v_mfma_f32_32x32x16_bf16 v[112:127], v[34:37], v[152:155], 0
	s_waitcnt lgkmcnt(0)
	v_mfma_f32_32x32x16_bf16 v[112:127], v[38:41], v[156:159], v[112:127]
	s_setprio 0
	ds_read_b128 v[34:37], v33 offset:64
	ds_read_b128 v[38:41], v33 offset:96
	s_setprio 1
	s_waitcnt lgkmcnt(1)
	v_mfma_f32_32x32x16_bf16 v[96:111], v[34:37], v[160:163], 0
	s_waitcnt lgkmcnt(0)
	v_mfma_f32_32x32x16_bf16 v[96:111], v[38:41], v[164:167], v[96:111]
	s_setprio 0
	s_andn2_b64 vcc, exec, s[0:1]
	v_add_f32_e32 v229, 0x41000000, v226
	s_cbranch_vccz .LBB0_796
	v_and_b32_e32 v33, 1, v32
	v_and_b32_e32 v34, 2, v32
	v_cmp_eq_u32_e64 s[0:1], 0, v33
	v_cmp_eq_u32_e64 s[38:39], 0, v34
	v_and_b32_e32 v36, 4, v32
	v_and_b32_e32 v37, 8, v32
	v_cndmask_b32_e64 v33, v112, v208, s[0:1]
	v_cndmask_b32_e64 v34, v113, v208, s[38:39]
	v_cmp_eq_u32_e64 s[40:41], 0, v36
	v_cmp_eq_u32_e64 s[42:43], 0, v37
	v_and_b32_e32 v38, 16, v32
	v_and_b32_e32 v39, 32, v32
	v_max3_f32 v35, v33, s15, v34
	v_cndmask_b32_e64 v36, v114, v208, s[40:41]
	v_cndmask_b32_e64 v37, v115, v208, s[42:43]
	v_cmp_eq_u32_e64 s[44:45], 0, v38
	v_cmp_eq_u32_e64 s[48:49], 0, v39
	v_and_b32_e32 v40, 64, v32
	v_and_b32_e32 v41, 0x80, v32
	v_max3_f32 v35, v35, v36, v37
	v_cndmask_b32_e64 v38, v116, v208, s[44:45]
	v_cndmask_b32_e64 v39, v117, v208, s[48:49]
	v_cmp_eq_u32_e64 s[50:51], 0, v40
	v_cmp_eq_u32_e64 s[52:53], 0, v41
	v_and_b32_e32 v42, 0x100, v32
	v_and_b32_e32 v43, 0x200, v32
	v_max3_f32 v35, v35, v38, v39
	v_cndmask_b32_e64 v40, v118, v208, s[50:51]
	v_cndmask_b32_e64 v41, v119, v208, s[52:53]
	v_cmp_eq_u32_e64 s[54:55], 0, v42
	v_cmp_eq_u32_e64 s[56:57], 0, v43
	v_and_b32_e32 v44, 0x400, v32
	v_and_b32_e32 v45, 0x800, v32
	v_max3_f32 v35, v35, v40, v41
	v_cndmask_b32_e64 v42, v120, v208, s[54:55]
	v_cndmask_b32_e64 v43, v121, v208, s[56:57]
	v_cmp_eq_u32_e64 s[58:59], 0, v44
	v_cmp_eq_u32_e64 s[60:61], 0, v45
	v_and_b32_e32 v46, 0x1000, v32
	v_and_b32_e32 v47, 0x2000, v32
	v_max3_f32 v35, v35, v42, v43
	v_cndmask_b32_e64 v44, v122, v208, s[58:59]
	v_cndmask_b32_e64 v45, v123, v208, s[60:61]
	v_cmp_eq_u32_e64 s[62:63], 0, v46
	v_cmp_eq_u32_e64 s[64:65], 0, v47
	v_and_b32_e32 v48, 0x4000, v32
	v_and_b32_e32 v32, 0x8000, v32
	v_max3_f32 v35, v35, v44, v45
	v_cndmask_b32_e64 v46, v124, v208, s[62:63]
	v_cndmask_b32_e64 v47, v125, v208, s[64:65]
	v_cmp_eq_u32_e64 s[66:67], 0, v48
	v_cmp_eq_u32_e64 s[68:69], 0, v32
	v_max3_f32 v35, v35, v46, v47
	v_cndmask_b32_e64 v48, v126, v208, s[66:67]
	v_cndmask_b32_e64 v32, v127, v208, s[68:69]
	v_max3_f32 v35, v35, v48, v32
	v_mov_b32_e32 v49, v35
	v_mov_b32_e32 v50, v35
	s_nop 1
	v_permlane32_swap_b32_e32 v49, v50
	v_cndmask_b32_e64 v49, v49, v50, s[36:37]
	v_max_f32_e32 v49, v49, v49
	v_max_f32_e32 v35, v35, v49
	v_cmp_gt_f32_e32 vcc, v35, v229
	v_mov_b32_e32 v228, v226
	v_mov_b32_e32 v192, v186
	v_cndmask_b32_e32 v130, v226, v35, vcc
	v_max_f32_e32 v35, v130, v130
	v_max_f32_e32 v35, 0xefa18f08, v35
	v_sub_f32_e32 v33, v33, v35
	v_exp_f32_e32 v128, v33
	v_sub_f32_e32 v33, v34, v35
	v_exp_f32_e32 v129, v33
	v_sub_f32_e32 v33, v36, v35
	v_exp_f32_e32 v131, v33
	v_sub_f32_e32 v33, v37, v35
	v_exp_f32_e32 v132, v33
	v_sub_f32_e32 v34, v38, v35
	v_add_f32_e32 v33, 0, v128
	v_exp_f32_e32 v133, v34
	v_sub_f32_e32 v34, v39, v35
	v_add_f32_e32 v33, v129, v33
	v_exp_f32_e32 v134, v34
	v_sub_f32_e32 v34, v40, v35
	v_add_f32_e32 v33, v131, v33
	v_exp_f32_e32 v135, v34
	v_sub_f32_e32 v34, v41, v35
	v_add_f32_e32 v33, v132, v33
	v_exp_f32_e32 v187, v34
	v_sub_f32_e32 v34, v42, v35
	v_add_f32_e32 v33, v133, v33
	v_exp_f32_e32 v189, v34
	v_sub_f32_e32 v34, v43, v35
	v_add_f32_e32 v33, v134, v33
	v_exp_f32_e32 v190, v34
	v_sub_f32_e32 v34, v44, v35
	v_add_f32_e32 v33, v135, v33
	v_exp_f32_e32 v191, v34
	v_sub_f32_e32 v34, v45, v35
	v_add_f32_e32 v33, v187, v33
	v_exp_f32_e32 v193, v34
	v_sub_f32_e32 v34, v46, v35
	v_add_f32_e32 v33, v189, v33
	v_exp_f32_e32 v230, v34
	v_sub_f32_e32 v34, v47, v35
	v_add_f32_e32 v33, v190, v33
	v_exp_f32_e32 v231, v34
	v_sub_f32_e32 v34, v48, v35
	v_add_f32_e32 v33, v191, v33
	v_exp_f32_e32 v232, v34
	v_sub_f32_e32 v32, v32, v35
	v_add_f32_e32 v33, v193, v33
	v_exp_f32_e32 v233, v32
	v_add_f32_e32 v32, v230, v33
	v_add_f32_e32 v32, v231, v32
	v_add_f32_e32 v32, v232, v32
	v_add_f32_e32 v188, v233, v32
	v_mov_b32_e32 v234, v188
	v_mov_b32_e32 v235, v188
	s_nop 0
	s_nop 0
	v_permlane32_swap_b32_e32 v234, v235
	v_cmp_neq_f32_e32 vcc, v130, v226
	s_cbranch_vccz .LBB0_795
	v_sub_f32_e32 v32, v226, v130
	v_exp_f32_e32 v32, v32
	v_mov_b32_e32 v228, v130
	v_mul_f32_e32 v192, v186, v32
	v_pk_mul_f32 v[30:31], v[30:31], v[32:33] op_sel_hi:[1,0]
	v_pk_mul_f32 v[28:29], v[28:29], v[32:33] op_sel_hi:[1,0]
	v_pk_mul_f32 v[26:27], v[26:27], v[32:33] op_sel_hi:[1,0]
	v_pk_mul_f32 v[24:25], v[24:25], v[32:33] op_sel_hi:[1,0]
	v_pk_mul_f32 v[22:23], v[22:23], v[32:33] op_sel_hi:[1,0]
	v_pk_mul_f32 v[20:21], v[20:21], v[32:33] op_sel_hi:[1,0]
	v_pk_mul_f32 v[18:19], v[18:19], v[32:33] op_sel_hi:[1,0]
	v_pk_mul_f32 v[16:17], v[16:17], v[32:33] op_sel_hi:[1,0]
	v_pk_mul_f32 v[14:15], v[14:15], v[32:33] op_sel_hi:[1,0]
	v_pk_mul_f32 v[12:13], v[12:13], v[32:33] op_sel_hi:[1,0]
	v_pk_mul_f32 v[10:11], v[10:11], v[32:33] op_sel_hi:[1,0]
	v_pk_mul_f32 v[8:9], v[8:9], v[32:33] op_sel_hi:[1,0]
	v_pk_mul_f32 v[6:7], v[6:7], v[32:33] op_sel_hi:[1,0]
	v_pk_mul_f32 v[4:5], v[4:5], v[32:33] op_sel_hi:[1,0]
	v_pk_mul_f32 v[2:3], v[2:3], v[32:33] op_sel_hi:[1,0]
	v_pk_mul_f32 v[0:1], v[0:1], v[32:33] op_sel_hi:[1,0]

; DI void pv_rows(f32x16 (&o)[2], LAS const char* Vl, int row0, const bf16x8 (&pf)[2], int lane) {
;     const int h = lane >> 5, i = lane & 15, grp = (lane >> 4) & 1;
;     LAS const char* base = Vl + (row0 + 4 * h + (i >> 2)) * KP + grp * 32 + (i & 3) * 8;
;     bf16x8 vf[2][2];
; #pragma unroll
;     for (int dt = 0; dt < 2; ++dt)
; #pragma unroll
;         for (int s2 = 0; s2 < 2; ++s2) {
;             const s16x4 lo = vtr(base + (16 * s2) * KP + dt * 64), hi = vtr(base + (16 * s2 + 8) * KP + dt * 64);
;             vf[dt][s2] = (bf16x8){lo[0], lo[1], lo[2], lo[3], hi[0], hi[1], hi[2], hi[3]};
;         }
;     __builtin_amdgcn_s_setprio(1);
; #pragma unroll
;     for (int s2 = 0; s2 < 2; ++s2)
; #pragma unroll
;         for (int dt = 0; dt < 2; ++dt) o[dt] = MFMA32(vf[dt][s2], pf[s2], o[dt]);
;     __builtin_amdgcn_s_setprio(0);
; }
; DI void pack_p(const float (&p)[16], bf16x8 (&pf)[2]) {
; #pragma unroll
;     for (int s2 = 0; s2 < 2; ++s2) { u32x4 w; w.x = cvtpk(p[8 * s2], p[8 * s2 + 1]); w.y = cvtpk(p[8 * s2 + 2], p[8 * s2 + 3]); w.z = cvtpk(p[8 * s2 + 4], p[8 * s2 + 5]); w.w = cvtpk(p[8 * s2 + 6], p[8 * s2 + 7]);
;         pf[s2] = __builtin_bit_cast(bf16x8, w); }
; }
; template <int MM> DI void smax_step(const f32x16& s, unsigned vm, float& m, float& l, f32x16 (&o)[2], bf16x8 (&pf)[2], int lane) {
;     float t[16], mx = -1e30f;
; #pragma unroll
;     for (int i = 0; i < 16; ++i) { t[i] = (MM == 0) ? s[i] : (MM == 1 ? (vm ? s[i] : -1e30f) : (((vm >> i) & 1u) ? s[i] : -1e30f)); mx = fmaxf(mx, t[i]); }
;     mx = fmaxf(mx, shx32(mx, lane));
;     const float mn = (mx > m + 8.0f) ? mx : m;
;     const float mref = fmaxf(mn, -1e29f);
;     float p[16], rs = 0.f;
; #pragma unroll
;     for (int i = 0; i < 16; ++i) { p[i] = ex2(t[i] - mref); rs += p[i]; }
;     rs += shx32(rs, lane);
;     if (__builtin_amdgcn_ballot_w64(mn != m) != 0ull) {
;         const float alpha = ex2(m - mn);
;         l *= alpha;
; #pragma unroll
;         for (int i = 0; i < 16; ++i) { o[0][i] *= alpha; o[1][i] *= alpha; }
;         m = mn;
;     }
;     l += rs;
;     pack_p(p, pf);
; template <int MODE, bool PRE = false> ...
;     ...
;                 if (mm == 0) { smax_step<0>(s1, vm, m1, l1, o1, pf, lane); smax_step<0>(s2, vm, m2, l2, o2, pf2, lane); }
;                 else { smax_step<2>(s1, vm, m1, l1, o1, pf, lane); smax_step<2>(s2, vm, m2, l2, o2, pf2, lane); }
.LBB0_800:
	v_cvt_pk_bf16_f32 v128, v32, v33
	v_max3_f32 v32, v96, s15, v97
	v_max3_f32 v32, v32, v98, v99
	v_max3_f32 v32, v32, v100, v101
	v_max3_f32 v32, v32, v102, v103
	v_max3_f32 v32, v32, v104, v105
	v_max3_f32 v32, v32, v106, v107
	v_max3_f32 v32, v32, v108, v109
	v_max3_f32 v32, v32, v110, v111
	v_cvt_pk_bf16_f32 v129, v34, v35
	v_mov_b32_e32 v33, v32
	v_mov_b32_e32 v34, v32
	s_nop 1
	v_permlane32_swap_b32_e32 v33, v34
	v_cndmask_b32_e64 v33, v33, v34, s[36:37]
	v_max_f32_e32 v33, v33, v33
	v_max_f32_e32 v32, v32, v33
	v_add_f32_e32 v33, 0x41000000, v224
	v_cmp_gt_f32_e32 vcc, v32, v33
	v_cndmask_b32_e64 v48, v48, v49, s[36:37]
	v_cvt_pk_bf16_f32 v130, v36, v37
	v_cndmask_b32_e32 v230, v224, v32, vcc
	v_max_f32_e32 v32, v230, v230
	v_max_f32_e32 v32, 0xefa18f08, v32
	v_sub_f32_e32 v33, v96, v32
	v_exp_f32_e32 v231, v33
	v_sub_f32_e32 v33, v97, v32
	v_exp_f32_e32 v232, v33
	v_sub_f32_e32 v33, v98, v32
	v_exp_f32_e32 v233, v33
	v_sub_f32_e32 v33, v99, v32
	v_exp_f32_e32 v234, v33
	v_sub_f32_e32 v34, v100, v32
	v_add_f32_e32 v33, 0, v231
	v_exp_f32_e32 v235, v34
	v_sub_f32_e32 v34, v101, v32
	v_add_f32_e32 v33, v232, v33
	v_exp_f32_e32 v236, v34
	v_sub_f32_e32 v34, v102, v32
	v_add_f32_e32 v33, v233, v33
	v_exp_f32_e32 v237, v34
	v_sub_f32_e32 v34, v103, v32
	v_add_f32_e32 v33, v234, v33
	v_exp_f32_e32 v238, v34
	v_sub_f32_e32 v34, v104, v32
	v_add_f32_e32 v33, v235, v33
	v_exp_f32_e32 v239, v34
	v_sub_f32_e32 v34, v105, v32
	v_add_f32_e32 v33, v236, v33
	v_exp_f32_e32 v240, v34
	v_sub_f32_e32 v34, v106, v32
	v_add_f32_e32 v33, v237, v33
	v_exp_f32_e32 v241, v34
	v_sub_f32_e32 v34, v107, v32
	v_add_f32_e32 v33, v238, v33
	v_exp_f32_e32 v242, v34
	v_sub_f32_e32 v34, v108, v32
	v_add_f32_e32 v33, v239, v33
	v_exp_f32_e32 v243, v34
	v_sub_f32_e32 v34, v109, v32
	v_add_f32_e32 v33, v240, v33
	v_exp_f32_e32 v244, v34
	v_sub_f32_e32 v34, v110, v32
	v_add_f32_e32 v33, v241, v33
	v_exp_f32_e32 v189, v34
	v_sub_f32_e32 v32, v111, v32
	v_add_f32_e32 v33, v242, v33
	v_exp_f32_e32 v187, v32
	v_add_f32_e32 v32, v243, v33
	v_add_f32_e32 v49, v244, v32
	v_pk_add_f32 v[32:33], v[188:189], v[48:49]
	v_cmp_neq_f32_e32 vcc, v230, v224
	v_pk_add_f32 v[190:191], v[32:33], v[186:187]
	v_cvt_pk_bf16_f32 v131, v38, v39
	v_cvt_pk_bf16_f32 v132, v40, v41
	v_cvt_pk_bf16_f32 v133, v42, v43
	v_cvt_pk_bf16_f32 v134, v44, v45
	v_cvt_pk_bf16_f32 v135, v46, v47
	v_mov_b32_e32 v188, v191
	v_mov_b32_e32 v192, v191
	s_cmp_lg_u64 vcc, 0
	s_nop 0
	v_permlane32_swap_b32_e32 v188, v192
	s_cselect_b64 s[0:1], -1, 0
.LBB0_801:
	s_and_b64 vcc, exec, s[0:1]
	s_cbranch_vccz .LBB0_803
	v_sub_f32_e32 v32, v224, v230
	v_exp_f32_e32 v32, v32
	v_mov_b32_e32 v224, v230
	v_mul_f32_e32 v217, v217, v32
	v_pk_mul_f32 v[78:79], v[78:79], v[32:33] op_sel_hi:[1,0]
	v_pk_mul_f32 v[76:77], v[76:77], v[32:33] op_sel_hi:[1,0]
	v_pk_mul_f32 v[74:75], v[74:75], v[32:33] op_sel_hi:[1,0]
	v_pk_mul_f32 v[72:73], v[72:73], v[32:33] op_sel_hi:[1,0]
	v_pk_mul_f32 v[70:71], v[70:71], v[32:33] op_sel_hi:[1,0]
	v_pk_mul_f32 v[68:69], v[68:69], v[32:33] op_sel_hi:[1,0]
	v_pk_mul_f32 v[66:67], v[66:67], v[32:33] op_sel_hi:[1,0]
	v_pk_mul_f32 v[64:65], v[64:65], v[32:33] op_sel_hi:[1,0]
	v_pk_mul_f32 v[94:95], v[94:95], v[32:33] op_sel_hi:[1,0]
	v_pk_mul_f32 v[92:93], v[92:93], v[32:33] op_sel_hi:[1,0]
	v_pk_mul_f32 v[90:91], v[90:91], v[32:33] op_sel_hi:[1,0]
	v_pk_mul_f32 v[88:89], v[88:89], v[32:33] op_sel_hi:[1,0]
	v_pk_mul_f32 v[86:87], v[86:87], v[32:33] op_sel_hi:[1,0]
	v_pk_mul_f32 v[84:85], v[84:85], v[32:33] op_sel_hi:[1,0]
	v_pk_mul_f32 v[82:83], v[82:83], v[32:33] op_sel_hi:[1,0]
	v_pk_mul_f32 v[80:81], v[80:81], v[32:33] op_sel_hi:[1,0]
.LBB0_803:
	v_add_u32_e32 v56, v225, v222
	ds_read_b64_tr_b16 v[40:41], v56 offset:9216
	ds_read_b64_tr_b16 v[42:43], v56 offset:10368
	ds_read_b64_tr_b16 v[44:45], v56 offset:11520
	ds_read_b64_tr_b16 v[46:47], v56 offset:12672
	ds_read_b64_tr_b16 v[48:49], v56 offset:9280
	ds_read_b64_tr_b16 v[50:51], v56 offset:10432
	ds_read_b64_tr_b16 v[52:53], v56 offset:11584
	ds_read_b64_tr_b16 v[54:55], v56 offset:12736
	v_cndmask_b32_e64 v32, v188, v192, s[36:37]
	v_add_f32_e32 v32, v191, v32
	v_add_f32_e32 v217, v217, v32
	v_cvt_pk_bf16_f32 v32, v231, v232
	v_cvt_pk_bf16_f32 v33, v233, v234
	v_cvt_pk_bf16_f32 v34, v235, v236
	v_cvt_pk_bf16_f32 v35, v237, v238
	v_cvt_pk_bf16_f32 v36, v239, v240
	v_cvt_pk_bf16_f32 v37, v241, v242
	v_cvt_pk_bf16_f32 v38, v243, v244
	v_cvt_pk_bf16_f32 v39, v189, v187
	s_setprio 1
	s_waitcnt lgkmcnt(6)
	v_mfma_f32_32x32x16_bf16 v[0:15], v[40:43], v[128:131], v[0:15]
	s_waitcnt lgkmcnt(2)
	v_mfma_f32_32x32x16_bf16 v[16:31], v[48:51], v[128:131], v[16:31]
	v_mfma_f32_32x32x16_bf16 v[0:15], v[44:47], v[132:135], v[0:15]
	s_waitcnt lgkmcnt(0)
	v_mfma_f32_32x32x16_bf16 v[16:31], v[52:55], v[132:135], v[16:31]
	s_setprio 0
	ds_read_b64_tr_b16 v[40:41], v56 offset:9216
	ds_read_b64_tr_b16 v[42:43], v56 offset:10368
	ds_read_b64_tr_b16 v[46:47], v56 offset:10432
	ds_read_b64_tr_b16 v[44:45], v56 offset:9280
	ds_read_b64_tr_b16 v[48:49], v56 offset:11520
	ds_read_b64_tr_b16 v[50:51], v56 offset:12672
	ds_read_b64_tr_b16 v[54:55], v56 offset:12736
	ds_read_b64_tr_b16 v[52:53], v56 offset:11584
	s_setprio 1
	s_waitcnt lgkmcnt(6)
	v_mfma_f32_32x32x16_bf16 v[64:79], v[40:43], v[32:35], v[64:79]
	s_waitcnt lgkmcnt(4)
	v_mfma_f32_32x32x16_bf16 v[80:95], v[44:47], v[32:35], v[80:95]
	s_waitcnt lgkmcnt(2)
	v_mfma_f32_32x32x16_bf16 v[64:79], v[48:51], v[36:39], v[64:79]
	s_waitcnt lgkmcnt(0)
	v_mfma_f32_32x32x16_bf16 v[80:95], v[52:55], v[36:39], v[80:95]
	s_setprio 0
	v_mov_b32_e32 v186, v190
	v_mov_b32_e32 v226, v228

; DI float ex2(float x) { return __builtin_amdgcn_exp2f(x); }
; template <int MM> DI void smax_step(const f32x16& s, unsigned vm, float& m, float& l, f32x16 (&o)[2], bf16x8 (&pf)[2], int lane) {
;     float t[16], mx = -1e30f;
; #pragma unroll
;     for (int i = 0; i < 16; ++i) { t[i] = (MM == 0) ? s[i] : (MM == 1 ? (vm ? s[i] : -1e30f) : (((vm >> i) & 1u) ? s[i] : -1e30f)); mx = fmaxf(mx, t[i]); }
;     mx = fmaxf(mx, shx32(mx, lane));
;     const float mn = (mx > m + 8.0f) ? mx : m;
;     const float mref = fmaxf(mn, -1e29f);
;     float p[16], rs = 0.f;
; #pragma unroll
;     for (int i = 0; i < 16; ++i) { p[i] = ex2(t[i] - mref); rs += p[i]; }
;     rs += shx32(rs, lane);
;     if (__builtin_amdgcn_ballot_w64(mn != m) != 0ull) {
;         const float alpha = ex2(m - mn);
;         l *= alpha;
; #pragma unroll
;         for (int i = 0; i < 16; ++i) { o[0][i] *= alpha; o[1][i] *= alpha; }
;         m = mn;
;     }
;     l += rs;
;     pack_p(p, pf);
; template <int MODE, bool PRE = false> ...
;     ...
;                 const f32x16 s1 = qk_rows<0, 2>(Kl, 32 * sub, qf, r, h), s2 = qk_rows<2, 4>(Kl, 32 * sub, qf, r, h);
;                 bf16x8 pf2[2];
;                 if (mm == 0) { smax_step<0>(s1, vm, m1, l1, o1, pf, lane); smax_step<0>(s2, vm, m2, l2, o2, pf2, lane); }
;                 else { smax_step<2>(s1, vm, m1, l1, o1, pf, lane); smax_step<2>(s2, vm, m2, l2, o2, pf2, lane); }
.LBB0_810:
	s_andn2_b64 vcc, exec, s[38:39]
	s_cbranch_vccnz .LBB0_823
	v_add_u32_e32 v33, v227, v223
	ds_read_b128 v[34:37], v33
	ds_read_b128 v[38:41], v33 offset:32
	s_setprio 1
	s_waitcnt lgkmcnt(1)
	v_mfma_f32_32x32x16_bf16 v[112:127], v[34:37], v[152:155], 0
	s_waitcnt lgkmcnt(0)
	v_mfma_f32_32x32x16_bf16 v[112:127], v[38:41], v[156:159], v[112:127]
	s_setprio 0
	ds_read_b128 v[34:37], v33 offset:64
	ds_read_b128 v[38:41], v33 offset:96
	s_setprio 1
	s_waitcnt lgkmcnt(1)
	v_mfma_f32_32x32x16_bf16 v[96:111], v[34:37], v[160:163], 0
	s_waitcnt lgkmcnt(0)
	v_mfma_f32_32x32x16_bf16 v[96:111], v[38:41], v[164:167], v[96:111]
	s_setprio 0
	s_and_b64 vcc, exec, s[0:1]
	v_add_f32_e32 v187, 0x41000000, v226
	s_cbranch_vccnz .LBB0_815
	v_and_b32_e32 v33, 1, v32
	v_and_b32_e32 v34, 2, v32
	v_cmp_eq_u32_e64 s[0:1], 0, v33
	v_cmp_eq_u32_e64 s[38:39], 0, v34
	v_and_b32_e32 v36, 4, v32
	v_and_b32_e32 v37, 8, v32
	v_cndmask_b32_e64 v33, v112, v208, s[0:1]
	v_cndmask_b32_e64 v34, v113, v208, s[38:39]
	v_cmp_eq_u32_e64 s[40:41], 0, v36
	v_cmp_eq_u32_e64 s[42:43], 0, v37
	v_and_b32_e32 v38, 16, v32
	v_and_b32_e32 v39, 32, v32
	v_max3_f32 v35, v33, s15, v34
	v_cndmask_b32_e64 v36, v114, v208, s[40:41]
	v_cndmask_b32_e64 v37, v115, v208, s[42:43]
	v_cmp_eq_u32_e64 s[44:45], 0, v38
	v_cmp_eq_u32_e64 s[48:49], 0, v39
	v_and_b32_e32 v40, 64, v32
	v_and_b32_e32 v41, 0x80, v32
	v_max3_f32 v35, v35, v36, v37
	v_cndmask_b32_e64 v38, v116, v208, s[44:45]
	v_cndmask_b32_e64 v39, v117, v208, s[48:49]
	v_cmp_eq_u32_e64 s[50:51], 0, v40
	v_cmp_eq_u32_e64 s[52:53], 0, v41
	v_and_b32_e32 v42, 0x100, v32
	v_and_b32_e32 v43, 0x200, v32
	v_max3_f32 v35, v35, v38, v39
	v_cndmask_b32_e64 v40, v118, v208, s[50:51]
	v_cndmask_b32_e64 v41, v119, v208, s[52:53]
	v_cmp_eq_u32_e64 s[54:55], 0, v42
	v_cmp_eq_u32_e64 s[56:57], 0, v43
	v_and_b32_e32 v44, 0x400, v32
	v_and_b32_e32 v45, 0x800, v32
	v_max3_f32 v35, v35, v40, v41
	v_cndmask_b32_e64 v42, v120, v208, s[54:55]
	v_cndmask_b32_e64 v43, v121, v208, s[56:57]
	v_cmp_eq_u32_e64 s[58:59], 0, v44
	v_cmp_eq_u32_e64 s[60:61], 0, v45
	v_and_b32_e32 v46, 0x1000, v32
	v_and_b32_e32 v47, 0x2000, v32
	v_max3_f32 v35, v35, v42, v43
	v_cndmask_b32_e64 v44, v122, v208, s[58:59]
	v_cndmask_b32_e64 v45, v123, v208, s[60:61]
	v_cmp_eq_u32_e64 s[62:63], 0, v46
	v_cmp_eq_u32_e64 s[64:65], 0, v47
	v_and_b32_e32 v48, 0x4000, v32
	v_and_b32_e32 v32, 0x8000, v32
	v_max3_f32 v35, v35, v44, v45
	v_cndmask_b32_e64 v46, v124, v208, s[62:63]
	v_cndmask_b32_e64 v47, v125, v208, s[64:65]
	v_cmp_eq_u32_e64 s[66:67], 0, v48
	v_cmp_eq_u32_e64 s[68:69], 0, v32
	v_max3_f32 v35, v35, v46, v47
	v_cndmask_b32_e64 v48, v126, v208, s[66:67]
	v_cndmask_b32_e64 v32, v127, v208, s[68:69]
	v_max3_f32 v35, v35, v48, v32
	v_mov_b32_e32 v49, v35
	v_mov_b32_e32 v50, v35
	s_nop 1
	v_permlane32_swap_b32_e32 v49, v50
	v_cndmask_b32_e64 v49, v49, v50, s[36:37]
	v_max_f32_e32 v49, v49, v49
	v_max_f32_e32 v35, v35, v49
	v_cmp_gt_f32_e32 vcc, v35, v187
	v_mov_b32_e32 v227, v226
	v_mov_b32_e32 v192, v186
	v_cndmask_b32_e32 v130, v226, v35, vcc
	v_max_f32_e32 v35, v130, v130
	v_max_f32_e32 v35, 0xefa18f08, v35
	v_sub_f32_e32 v33, v33, v35
	v_exp_f32_e32 v128, v33
	v_sub_f32_e32 v33, v34, v35
	v_exp_f32_e32 v129, v33
	v_sub_f32_e32 v33, v36, v35
	v_exp_f32_e32 v131, v33
	v_sub_f32_e32 v33, v37, v35
	v_exp_f32_e32 v132, v33
	v_sub_f32_e32 v34, v38, v35
	v_add_f32_e32 v33, 0, v128
	v_exp_f32_e32 v133, v34
	v_sub_f32_e32 v34, v39, v35
	v_add_f32_e32 v33, v129, v33
	v_exp_f32_e32 v134, v34
	v_sub_f32_e32 v34, v40, v35
	v_add_f32_e32 v33, v131, v33
	v_exp_f32_e32 v135, v34
	v_sub_f32_e32 v34, v41, v35
	v_add_f32_e32 v33, v132, v33
	v_exp_f32_e32 v189, v34
	v_sub_f32_e32 v34, v42, v35
	v_add_f32_e32 v33, v133, v33
	v_exp_f32_e32 v190, v34
	v_sub_f32_e32 v34, v43, v35
	v_add_f32_e32 v33, v134, v33
	v_exp_f32_e32 v191, v34
	v_sub_f32_e32 v34, v44, v35
	v_add_f32_e32 v33, v135, v33
	v_exp_f32_e32 v193, v34
	v_sub_f32_e32 v34, v45, v35
	v_add_f32_e32 v33, v189, v33
	v_exp_f32_e32 v228, v34
	v_sub_f32_e32 v34, v46, v35
	v_add_f32_e32 v33, v190, v33
	v_exp_f32_e32 v229, v34
	v_sub_f32_e32 v34, v47, v35
	v_add_f32_e32 v33, v191, v33
	v_exp_f32_e32 v230, v34
	v_sub_f32_e32 v34, v48, v35
	v_add_f32_e32 v33, v193, v33
	v_exp_f32_e32 v231, v34
	v_sub_f32_e32 v32, v32, v35
	v_add_f32_e32 v33, v228, v33
	v_exp_f32_e32 v232, v32
	v_add_f32_e32 v32, v229, v33
	v_add_f32_e32 v32, v230, v32
	v_add_f32_e32 v32, v231, v32
	v_add_f32_e32 v188, v232, v32
	v_mov_b32_e32 v233, v188
	v_mov_b32_e32 v234, v188
	s_nop 0
	s_nop 0
	v_permlane32_swap_b32_e32 v233, v234
	v_cmp_neq_f32_e32 vcc, v130, v226
	s_cbranch_vccz .LBB0_814
	v_sub_f32_e32 v32, v226, v130
	v_exp_f32_e32 v32, v32
	v_mov_b32_e32 v227, v130
	v_mul_f32_e32 v192, v186, v32
	v_pk_mul_f32 v[30:31], v[30:31], v[32:33] op_sel_hi:[1,0]
	v_pk_mul_f32 v[28:29], v[28:29], v[32:33] op_sel_hi:[1,0]
	v_pk_mul_f32 v[26:27], v[26:27], v[32:33] op_sel_hi:[1,0]
	v_pk_mul_f32 v[24:25], v[24:25], v[32:33] op_sel_hi:[1,0]
	v_pk_mul_f32 v[22:23], v[22:23], v[32:33] op_sel_hi:[1,0]
	v_pk_mul_f32 v[20:21], v[20:21], v[32:33] op_sel_hi:[1,0]
	v_pk_mul_f32 v[18:19], v[18:19], v[32:33] op_sel_hi:[1,0]
	v_pk_mul_f32 v[16:17], v[16:17], v[32:33] op_sel_hi:[1,0]
	v_pk_mul_f32 v[14:15], v[14:15], v[32:33] op_sel_hi:[1,0]
	v_pk_mul_f32 v[12:13], v[12:13], v[32:33] op_sel_hi:[1,0]
	v_pk_mul_f32 v[10:11], v[10:11], v[32:33] op_sel_hi:[1,0]
	v_pk_mul_f32 v[8:9], v[8:9], v[32:33] op_sel_hi:[1,0]
	v_pk_mul_f32 v[6:7], v[6:7], v[32:33] op_sel_hi:[1,0]
	v_pk_mul_f32 v[4:5], v[4:5], v[32:33] op_sel_hi:[1,0]
	v_pk_mul_f32 v[2:3], v[2:3], v[32:33] op_sel_hi:[1,0]
	v_pk_mul_f32 v[0:1], v[0:1], v[32:33] op_sel_hi:[1,0]

; DI void pv_rows(f32x16 (&o)[2], LAS const char* Vl, int row0, const bf16x8 (&pf)[2], int lane) {
;     const int h = lane >> 5, i = lane & 15, grp = (lane >> 4) & 1;
;     LAS const char* base = Vl + (row0 + 4 * h + (i >> 2)) * KP + grp * 32 + (i & 3) * 8;
;     bf16x8 vf[2][2];
; #pragma unroll
;     for (int dt = 0; dt < 2; ++dt)
; #pragma unroll
;         for (int s2 = 0; s2 < 2; ++s2) {
;             const s16x4 lo = vtr(base + (16 * s2) * KP + dt * 64), hi = vtr(base + (16 * s2 + 8) * KP + dt * 64);
;             vf[dt][s2] = (bf16x8){lo[0], lo[1], lo[2], lo[3], hi[0], hi[1], hi[2], hi[3]};
;         }
;     __builtin_amdgcn_s_setprio(1);
; #pragma unroll
;     for (int s2 = 0; s2 < 2; ++s2)
; #pragma unroll
;         for (int dt = 0; dt < 2; ++dt) o[dt] = MFMA32(vf[dt][s2], pf[s2], o[dt]);
;     __builtin_amdgcn_s_setprio(0);
; }
; DI void pack_p(const float (&p)[16], bf16x8 (&pf)[2]) {
; #pragma unroll
;     for (int s2 = 0; s2 < 2; ++s2) { u32x4 w; w.x = cvtpk(p[8 * s2], p[8 * s2 + 1]); w.y = cvtpk(p[8 * s2 + 2], p[8 * s2 + 3]); w.z = cvtpk(p[8 * s2 + 4], p[8 * s2 + 5]); w.w = cvtpk(p[8 * s2 + 6], p[8 * s2 + 7]);
;         pf[s2] = __builtin_bit_cast(bf16x8, w); }
; }
; template <int MM> DI void smax_step(const f32x16& s, unsigned vm, float& m, float& l, f32x16 (&o)[2], bf16x8 (&pf)[2], int lane) {
;     float t[16], mx = -1e30f;
; #pragma unroll
;     for (int i = 0; i < 16; ++i) { t[i] = (MM == 0) ? s[i] : (MM == 1 ? (vm ? s[i] : -1e30f) : (((vm >> i) & 1u) ? s[i] : -1e30f)); mx = fmaxf(mx, t[i]); }
;     mx = fmaxf(mx, shx32(mx, lane));
;     const float mn = (mx > m + 8.0f) ? mx : m;
;     const float mref = fmaxf(mn, -1e29f);
;     float p[16], rs = 0.f;
; #pragma unroll
;     for (int i = 0; i < 16; ++i) { p[i] = ex2(t[i] - mref); rs += p[i]; }
;     rs += shx32(rs, lane);
;     if (__builtin_amdgcn_ballot_w64(mn != m) != 0ull) {
;         const float alpha = ex2(m - mn);
;         l *= alpha;
; #pragma unroll
;         for (int i = 0; i < 16; ++i) { o[0][i] *= alpha; o[1][i] *= alpha; }
;         m = mn;
;     }
;     l += rs;
;     pack_p(p, pf);
; template <int MODE, bool PRE = false> ...
;     ...
;                 if (mm == 0) { smax_step<0>(s1, vm, m1, l1, o1, pf, lane); smax_step<0>(s2, vm, m2, l2, o2, pf2, lane); }
;                 else { smax_step<2>(s1, vm, m1, l1, o1, pf, lane); smax_step<2>(s2, vm, m2, l2, o2, pf2, lane); }
.LBB0_819:
	v_cvt_pk_bf16_f32 v128, v32, v33
	v_max3_f32 v32, v96, s15, v97
	v_max3_f32 v32, v32, v98, v99
	v_max3_f32 v32, v32, v100, v101
	v_max3_f32 v32, v32, v102, v103
	v_max3_f32 v32, v32, v104, v105
	v_max3_f32 v32, v32, v106, v107
	v_max3_f32 v32, v32, v108, v109
	v_max3_f32 v32, v32, v110, v111
	v_cvt_pk_bf16_f32 v129, v34, v35
	v_mov_b32_e32 v33, v32
	v_mov_b32_e32 v34, v32
	s_nop 1
	v_permlane32_swap_b32_e32 v33, v34
	v_cndmask_b32_e64 v33, v33, v34, s[36:37]
	v_max_f32_e32 v33, v33, v33
	v_max_f32_e32 v32, v32, v33
	v_add_f32_e32 v33, 0x41000000, v224
	v_cmp_gt_f32_e32 vcc, v32, v33
	v_cndmask_b32_e64 v48, v48, v49, s[36:37]
	v_cvt_pk_bf16_f32 v130, v36, v37
	v_cndmask_b32_e32 v228, v224, v32, vcc
	v_max_f32_e32 v32, v228, v228
	v_max_f32_e32 v32, 0xefa18f08, v32
	v_sub_f32_e32 v33, v96, v32
	v_exp_f32_e32 v229, v33
	v_sub_f32_e32 v33, v97, v32
	v_exp_f32_e32 v230, v33
	v_sub_f32_e32 v33, v98, v32
	v_exp_f32_e32 v231, v33
	v_sub_f32_e32 v33, v99, v32
	v_exp_f32_e32 v232, v33
	v_sub_f32_e32 v34, v100, v32
	v_add_f32_e32 v33, 0, v229
	v_exp_f32_e32 v233, v34
	v_sub_f32_e32 v34, v101, v32
	v_add_f32_e32 v33, v230, v33
	v_exp_f32_e32 v234, v34
	v_sub_f32_e32 v34, v102, v32
	v_add_f32_e32 v33, v231, v33
	v_exp_f32_e32 v235, v34
	v_sub_f32_e32 v34, v103, v32
	v_add_f32_e32 v33, v232, v33
	v_exp_f32_e32 v236, v34
	v_sub_f32_e32 v34, v104, v32
	v_add_f32_e32 v33, v233, v33
	v_exp_f32_e32 v237, v34
	v_sub_f32_e32 v34, v105, v32
	v_add_f32_e32 v33, v234, v33
	v_exp_f32_e32 v238, v34
	v_sub_f32_e32 v34, v106, v32
	v_add_f32_e32 v33, v235, v33
	v_exp_f32_e32 v239, v34
	v_sub_f32_e32 v34, v107, v32
	v_add_f32_e32 v33, v236, v33
	v_exp_f32_e32 v240, v34
	v_sub_f32_e32 v34, v108, v32
	v_add_f32_e32 v33, v237, v33
	v_exp_f32_e32 v241, v34
	v_sub_f32_e32 v34, v109, v32
	v_add_f32_e32 v33, v238, v33
	v_exp_f32_e32 v242, v34
	v_sub_f32_e32 v34, v110, v32
	v_add_f32_e32 v33, v239, v33
	v_exp_f32_e32 v189, v34
	v_sub_f32_e32 v32, v111, v32
	v_add_f32_e32 v33, v240, v33
	v_exp_f32_e32 v187, v32
	v_add_f32_e32 v32, v241, v33
	v_add_f32_e32 v49, v242, v32
	v_pk_add_f32 v[32:33], v[188:189], v[48:49]
	v_cmp_neq_f32_e32 vcc, v228, v224
	v_pk_add_f32 v[190:191], v[32:33], v[186:187]
	v_cvt_pk_bf16_f32 v131, v38, v39
	v_cvt_pk_bf16_f32 v132, v40, v41
	v_cvt_pk_bf16_f32 v133, v42, v43
	v_cvt_pk_bf16_f32 v134, v44, v45
	v_cvt_pk_bf16_f32 v135, v46, v47
	v_mov_b32_e32 v188, v191
	v_mov_b32_e32 v192, v191
	s_cmp_lg_u64 vcc, 0
	s_nop 0
	v_permlane32_swap_b32_e32 v188, v192
	s_cselect_b64 s[0:1], -1, 0
	v_mov_b32_e32 v193, v187
.LBB0_820:
	s_and_b64 vcc, exec, s[0:1]
	s_cbranch_vccz .LBB0_822
	v_sub_f32_e32 v32, v224, v228
	v_exp_f32_e32 v32, v32
	v_mov_b32_e32 v224, v228
	v_mul_f32_e32 v217, v217, v32
	v_pk_mul_f32 v[78:79], v[78:79], v[32:33] op_sel_hi:[1,0]
	v_pk_mul_f32 v[76:77], v[76:77], v[32:33] op_sel_hi:[1,0]
	v_pk_mul_f32 v[74:75], v[74:75], v[32:33] op_sel_hi:[1,0]
	v_pk_mul_f32 v[72:73], v[72:73], v[32:33] op_sel_hi:[1,0]
	v_pk_mul_f32 v[70:71], v[70:71], v[32:33] op_sel_hi:[1,0]
	v_pk_mul_f32 v[68:69], v[68:69], v[32:33] op_sel_hi:[1,0]
	v_pk_mul_f32 v[66:67], v[66:67], v[32:33] op_sel_hi:[1,0]
	v_pk_mul_f32 v[64:65], v[64:65], v[32:33] op_sel_hi:[1,0]
	v_pk_mul_f32 v[94:95], v[94:95], v[32:33] op_sel_hi:[1,0]
	v_pk_mul_f32 v[92:93], v[92:93], v[32:33] op_sel_hi:[1,0]
	v_pk_mul_f32 v[90:91], v[90:91], v[32:33] op_sel_hi:[1,0]
	v_pk_mul_f32 v[88:89], v[88:89], v[32:33] op_sel_hi:[1,0]
	v_pk_mul_f32 v[86:87], v[86:87], v[32:33] op_sel_hi:[1,0]
	v_pk_mul_f32 v[84:85], v[84:85], v[32:33] op_sel_hi:[1,0]
	v_pk_mul_f32 v[82:83], v[82:83], v[32:33] op_sel_hi:[1,0]
	v_pk_mul_f32 v[80:81], v[80:81], v[32:33] op_sel_hi:[1,0]
.LBB0_822:
	v_add_u32_e32 v56, v225, v222
	ds_read_b64_tr_b16 v[40:41], v56 offset:13824
	ds_read_b64_tr_b16 v[42:43], v56 offset:14976
	ds_read_b64_tr_b16 v[44:45], v56 offset:16128
	ds_read_b64_tr_b16 v[46:47], v56 offset:17280
	ds_read_b64_tr_b16 v[48:49], v56 offset:13888
	ds_read_b64_tr_b16 v[50:51], v56 offset:15040
	ds_read_b64_tr_b16 v[52:53], v56 offset:16192
	ds_read_b64_tr_b16 v[54:55], v56 offset:17344
	v_cndmask_b32_e64 v32, v188, v192, s[36:37]
	v_add_f32_e32 v32, v191, v32
	v_add_f32_e32 v217, v217, v32
	v_cvt_pk_bf16_f32 v32, v229, v230
	v_cvt_pk_bf16_f32 v33, v231, v232
	v_cvt_pk_bf16_f32 v34, v233, v234
	v_cvt_pk_bf16_f32 v35, v235, v236
	v_cvt_pk_bf16_f32 v36, v237, v238
	v_cvt_pk_bf16_f32 v37, v239, v240
	v_cvt_pk_bf16_f32 v38, v241, v242
	v_cvt_pk_bf16_f32 v39, v189, v193
	s_setprio 1
	s_waitcnt lgkmcnt(6)
	v_mfma_f32_32x32x16_bf16 v[0:15], v[40:43], v[128:131], v[0:15]
	s_waitcnt lgkmcnt(2)
	v_mfma_f32_32x32x16_bf16 v[16:31], v[48:51], v[128:131], v[16:31]
	v_mfma_f32_32x32x16_bf16 v[0:15], v[44:47], v[132:135], v[0:15]
	s_waitcnt lgkmcnt(0)
	v_mfma_f32_32x32x16_bf16 v[16:31], v[52:55], v[132:135], v[16:31]
	s_setprio 0
	ds_read_b64_tr_b16 v[40:41], v56 offset:13824
	ds_read_b64_tr_b16 v[42:43], v56 offset:14976
	ds_read_b64_tr_b16 v[46:47], v56 offset:15040
	ds_read_b64_tr_b16 v[44:45], v56 offset:13888
	ds_read_b64_tr_b16 v[48:49], v56 offset:16128
	ds_read_b64_tr_b16 v[50:51], v56 offset:17280
	ds_read_b64_tr_b16 v[54:55], v56 offset:17344
	ds_read_b64_tr_b16 v[52:53], v56 offset:16192
	s_setprio 1
	s_waitcnt lgkmcnt(6)
	v_mfma_f32_32x32x16_bf16 v[64:79], v[40:43], v[32:35], v[64:79]
	s_waitcnt lgkmcnt(4)
	v_mfma_f32_32x32x16_bf16 v[80:95], v[44:47], v[32:35], v[80:95]
	s_waitcnt lgkmcnt(2)
	v_mfma_f32_32x32x16_bf16 v[64:79], v[48:51], v[36:39], v[64:79]
	s_waitcnt lgkmcnt(0)
	v_mfma_f32_32x32x16_bf16 v[80:95], v[52:55], v[36:39], v[80:95]
	s_setprio 0
	v_mov_b32_e32 v186, v190
	v_mov_b32_e32 v226, v227
